# MoE down-proj epilogue: row-scale loads batched up front (no per-row-group drain)
# speedup vs baseline: 1.0194x; 1.0068x over previous
.LBB0_1162:
	v_lshl_add_u32 v154, s36, 8, v148
	v_ashrrev_i32_e32 v155, 31, v154
	v_lshl_add_u64 v[144:145], v[154:155], 2, s[12:13]
	global_load_dword v228, v[144:145], off
	global_load_dword v230, v[144:145], off offset:64
	global_load_dword v232, v[144:145], off offset:128
	global_load_dword v234, v[144:145], off offset:192
	global_load_dword v236, v[144:145], off offset:512
	global_load_dword v238, v[144:145], off offset:576
	global_load_dword v240, v[144:145], off offset:640
	global_load_dword v242, v[144:145], off offset:704
	v_lshl_or_b32 v146, s63, 8, v150
	v_ashrrev_i32_e32 v147, 31, v146
	v_lshlrev_b64 v[160:161], 11, v[154:155]
	v_or_b32_e32 v158, 16, v154
	v_lshlrev_b64 v[162:163], 1, v[146:147]
	v_lshl_add_u64 v[146:147], s[10:11], 0, v[160:161]
	v_ashrrev_i32_e32 v159, 31, v158
	v_lshl_add_u64 v[146:147], v[146:147], 0, v[162:163]
	v_lshl_add_u64 v[160:161], v[158:159], 2, s[12:13]
	s_waitcnt vmcnt(0)
	v_pk_mul_f32 v[126:127], v[126:127], v[228:229] op_sel_hi:[1,0]
	v_pk_mul_f32 v[124:125], v[124:125], v[228:229] op_sel_hi:[1,0]
	v_pk_mul_f32 v[122:123], v[122:123], v[228:229] op_sel_hi:[1,0]
	v_pk_mul_f32 v[120:121], v[120:121], v[228:229] op_sel_hi:[1,0]
	v_pk_mul_f32 v[118:119], v[118:119], v[228:229] op_sel_hi:[1,0]
	v_pk_mul_f32 v[116:117], v[116:117], v[228:229] op_sel_hi:[1,0]
	v_pk_mul_f32 v[164:165], v[114:115], v[228:229] op_sel_hi:[1,0]
	v_pk_mul_f32 v[156:157], v[112:113], v[228:229] op_sel_hi:[1,0]
	v_cvt_pk_bf16_f32 v112, v124, v125
	v_cvt_pk_bf16_f32 v113, v126, v127
	v_cvt_pk_bf16_f32 v114, v120, v121
	v_cvt_pk_bf16_f32 v115, v122, v123
	global_store_dwordx4 v[146:147], v[112:115], off
	s_nop 1
	v_cvt_pk_bf16_f32 v112, v116, v117
	v_cvt_pk_bf16_f32 v113, v118, v119
	v_cvt_pk_bf16_f32 v114, v156, v157
	v_cvt_pk_bf16_f32 v115, v164, v165
	global_store_dwordx4 v[146:147], v[112:115], off offset:256
	s_nop 0
	v_lshlrev_b64 v[116:117], 11, v[158:159]
	v_or_b32_e32 v114, 32, v154
	v_lshl_add_u64 v[116:117], s[10:11], 0, v[116:117]
	v_ashrrev_i32_e32 v115, 31, v114
	v_lshl_add_u64 v[116:117], v[116:117], 0, v[162:163]
	v_lshl_add_u64 v[118:119], v[114:115], 2, s[12:13]
	s_nop 0
	v_pk_mul_f32 v[110:111], v[110:111], v[230:231] op_sel_hi:[1,0]
	v_pk_mul_f32 v[108:109], v[108:109], v[230:231] op_sel_hi:[1,0]
	v_pk_mul_f32 v[106:107], v[106:107], v[230:231] op_sel_hi:[1,0]
	v_pk_mul_f32 v[104:105], v[104:105], v[230:231] op_sel_hi:[1,0]
	v_pk_mul_f32 v[102:103], v[102:103], v[230:231] op_sel_hi:[1,0]
	v_pk_mul_f32 v[100:101], v[100:101], v[230:231] op_sel_hi:[1,0]
	v_pk_mul_f32 v[120:121], v[98:99], v[230:231] op_sel_hi:[1,0]
	v_pk_mul_f32 v[112:113], v[96:97], v[230:231] op_sel_hi:[1,0]
	v_cvt_pk_bf16_f32 v96, v108, v109
	v_cvt_pk_bf16_f32 v97, v110, v111
	v_cvt_pk_bf16_f32 v98, v104, v105
	v_cvt_pk_bf16_f32 v99, v106, v107
	global_store_dwordx4 v[116:117], v[96:99], off
	s_nop 1
	v_cvt_pk_bf16_f32 v96, v100, v101
	v_cvt_pk_bf16_f32 v97, v102, v103
	v_cvt_pk_bf16_f32 v98, v112, v113
	v_cvt_pk_bf16_f32 v99, v120, v121
	global_store_dwordx4 v[116:117], v[96:99], off offset:256
	s_nop 0
	v_lshlrev_b64 v[100:101], 11, v[114:115]
	v_or_b32_e32 v98, 48, v154
	v_lshl_add_u64 v[100:101], s[10:11], 0, v[100:101]
	v_ashrrev_i32_e32 v99, 31, v98
	v_lshl_add_u64 v[100:101], v[100:101], 0, v[162:163]
	v_lshl_add_u64 v[102:103], v[98:99], 2, s[12:13]
	s_nop 0
	v_pk_mul_f32 v[94:95], v[94:95], v[232:233] op_sel_hi:[1,0]
	v_pk_mul_f32 v[92:93], v[92:93], v[232:233] op_sel_hi:[1,0]
	v_pk_mul_f32 v[90:91], v[90:91], v[232:233] op_sel_hi:[1,0]
	v_pk_mul_f32 v[88:89], v[88:89], v[232:233] op_sel_hi:[1,0]
	v_pk_mul_f32 v[82:83], v[82:83], v[232:233] op_sel_hi:[1,0]
	v_pk_mul_f32 v[80:81], v[80:81], v[232:233] op_sel_hi:[1,0]
	v_pk_mul_f32 v[104:105], v[74:75], v[232:233] op_sel_hi:[1,0]
	v_pk_mul_f32 v[96:97], v[72:73], v[232:233] op_sel_hi:[1,0]
	v_cvt_pk_bf16_f32 v72, v92, v93
	v_cvt_pk_bf16_f32 v73, v94, v95
	v_cvt_pk_bf16_f32 v74, v88, v89
	v_cvt_pk_bf16_f32 v75, v90, v91
	global_store_dwordx4 v[100:101], v[72:75], off
	s_nop 1
	v_cvt_pk_bf16_f32 v72, v80, v81
	v_cvt_pk_bf16_f32 v73, v82, v83
	v_cvt_pk_bf16_f32 v74, v96, v97
	v_cvt_pk_bf16_f32 v75, v104, v105
	global_store_dwordx4 v[100:101], v[72:75], off offset:256
	s_nop 0
	s_nop 0
	v_pk_mul_f32 v[80:81], v[86:87], v[234:235] op_sel_hi:[1,0]
	v_lshlrev_b64 v[74:75], 11, v[98:99]
	v_lshl_add_u64 v[74:75], s[10:11], 0, v[74:75]
	v_lshl_add_u64 v[74:75], v[74:75], 0, v[162:163]
	v_pk_mul_f32 v[82:83], v[84:85], v[234:235] op_sel_hi:[1,0]
	v_pk_mul_f32 v[78:79], v[78:79], v[234:235] op_sel_hi:[1,0]
	v_pk_mul_f32 v[76:77], v[76:77], v[234:235] op_sel_hi:[1,0]
	v_pk_mul_f32 v[70:71], v[70:71], v[234:235] op_sel_hi:[1,0]
	v_pk_mul_f32 v[68:69], v[68:69], v[234:235] op_sel_hi:[1,0]
	v_pk_mul_f32 v[84:85], v[66:67], v[234:235] op_sel_hi:[1,0]
	v_pk_mul_f32 v[72:73], v[64:65], v[234:235] op_sel_hi:[1,0]
	v_cvt_pk_bf16_f32 v64, v82, v83
	v_cvt_pk_bf16_f32 v65, v80, v81
	v_cvt_pk_bf16_f32 v66, v76, v77
	v_cvt_pk_bf16_f32 v67, v78, v79
	global_store_dwordx4 v[74:75], v[64:67], off
	s_nop 1
	v_cvt_pk_bf16_f32 v64, v68, v69
	v_cvt_pk_bf16_f32 v65, v70, v71
	v_cvt_pk_bf16_f32 v66, v72, v73
	v_cvt_pk_bf16_f32 v67, v84, v85
	global_store_dwordx4 v[74:75], v[64:67], off offset:256
	s_nop 0
	v_add_co_u32_e32 v68, vcc, s59, v146
	v_lshl_add_u64 v[66:67], v[146:147], 0, s[6:7]
	s_nop 0
	v_addc_co_u32_e32 v69, vcc, 0, v147, vcc
	s_nop 0
	v_pk_mul_f32 v[62:63], v[62:63], v[236:237] op_sel_hi:[1,0]
	v_pk_mul_f32 v[60:61], v[60:61], v[236:237] op_sel_hi:[1,0]
	v_pk_mul_f32 v[58:59], v[58:59], v[236:237] op_sel_hi:[1,0]
	v_pk_mul_f32 v[56:57], v[56:57], v[236:237] op_sel_hi:[1,0]
	v_pk_mul_f32 v[54:55], v[54:55], v[236:237] op_sel_hi:[1,0]
	v_pk_mul_f32 v[52:53], v[52:53], v[236:237] op_sel_hi:[1,0]
	v_pk_mul_f32 v[70:71], v[50:51], v[236:237] op_sel_hi:[1,0]
	v_pk_mul_f32 v[64:65], v[48:49], v[236:237] op_sel_hi:[1,0]
	v_cvt_pk_bf16_f32 v48, v60, v61
	v_cvt_pk_bf16_f32 v49, v62, v63
	v_cvt_pk_bf16_f32 v50, v56, v57
	v_cvt_pk_bf16_f32 v51, v58, v59
	global_store_dwordx4 v[68:69], v[48:51], off
	s_nop 1
	v_cvt_pk_bf16_f32 v48, v52, v53
	v_cvt_pk_bf16_f32 v49, v54, v55
	v_cvt_pk_bf16_f32 v50, v64, v65
	v_cvt_pk_bf16_f32 v51, v70, v71
	global_store_dwordx4 v[66:67], v[48:51], off offset:256
	s_nop 0
	v_add_co_u32_e32 v52, vcc, s60, v146
	v_lshl_add_u64 v[50:51], v[146:147], 0, s[18:19]
	s_nop 0
	v_addc_co_u32_e32 v53, vcc, 0, v147, vcc
	s_nop 0
	v_pk_mul_f32 v[46:47], v[46:47], v[238:239] op_sel_hi:[1,0]
	v_pk_mul_f32 v[44:45], v[44:45], v[238:239] op_sel_hi:[1,0]
	v_pk_mul_f32 v[42:43], v[42:43], v[238:239] op_sel_hi:[1,0]
	v_pk_mul_f32 v[40:41], v[40:41], v[238:239] op_sel_hi:[1,0]
	v_pk_mul_f32 v[38:39], v[38:39], v[238:239] op_sel_hi:[1,0]
	v_pk_mul_f32 v[36:37], v[36:37], v[238:239] op_sel_hi:[1,0]
	v_pk_mul_f32 v[54:55], v[34:35], v[238:239] op_sel_hi:[1,0]
	v_pk_mul_f32 v[48:49], v[32:33], v[238:239] op_sel_hi:[1,0]
	v_cvt_pk_bf16_f32 v32, v44, v45
	v_cvt_pk_bf16_f32 v33, v46, v47
	v_cvt_pk_bf16_f32 v34, v40, v41
	v_cvt_pk_bf16_f32 v35, v42, v43
	global_store_dwordx4 v[52:53], v[32:35], off
	s_nop 1
	v_cvt_pk_bf16_f32 v32, v36, v37
	v_cvt_pk_bf16_f32 v33, v38, v39
	v_cvt_pk_bf16_f32 v34, v48, v49
	v_cvt_pk_bf16_f32 v35, v54, v55
	global_store_dwordx4 v[50:51], v[32:35], off offset:256
	s_nop 0
	v_add_co_u32_e32 v36, vcc, s61, v146
	v_lshl_add_u64 v[34:35], v[146:147], 0, s[20:21]
	s_nop 0
	v_addc_co_u32_e32 v37, vcc, 0, v147, vcc
	s_and_b64 vcc, exec, s[2:3]
	s_nop 0
	v_pk_mul_f32 v[30:31], v[30:31], v[240:241] op_sel_hi:[1,0]
	v_pk_mul_f32 v[28:29], v[28:29], v[240:241] op_sel_hi:[1,0]
	v_pk_mul_f32 v[26:27], v[26:27], v[240:241] op_sel_hi:[1,0]
	v_pk_mul_f32 v[24:25], v[24:25], v[240:241] op_sel_hi:[1,0]
	v_pk_mul_f32 v[22:23], v[22:23], v[240:241] op_sel_hi:[1,0]
	v_pk_mul_f32 v[20:21], v[20:21], v[240:241] op_sel_hi:[1,0]
	v_pk_mul_f32 v[38:39], v[18:19], v[240:241] op_sel_hi:[1,0]
	v_pk_mul_f32 v[32:33], v[16:17], v[240:241] op_sel_hi:[1,0]
	v_cvt_pk_bf16_f32 v16, v28, v29
	v_cvt_pk_bf16_f32 v17, v30, v31
	v_cvt_pk_bf16_f32 v18, v24, v25
	v_cvt_pk_bf16_f32 v19, v26, v27
	global_store_dwordx4 v[36:37], v[16:19], off
	s_nop 1
	v_cvt_pk_bf16_f32 v16, v20, v21
	v_cvt_pk_bf16_f32 v17, v22, v23
	v_cvt_pk_bf16_f32 v18, v32, v33
	v_cvt_pk_bf16_f32 v19, v38, v39
	global_store_dwordx4 v[34:35], v[16:19], off offset:256
	s_nop 0
	v_add_co_u32_e64 v20, s[0:1], s62, v146
	v_lshl_add_u64 v[18:19], v[146:147], 0, s[22:23]
	s_nop 0
	v_addc_co_u32_e64 v21, s[0:1], 0, v147, s[0:1]
	s_mov_b64 s[0:1], -1
	s_nop 0
	v_pk_mul_f32 v[14:15], v[14:15], v[242:243] op_sel_hi:[1,0]
	v_pk_mul_f32 v[12:13], v[12:13], v[242:243] op_sel_hi:[1,0]
	v_pk_mul_f32 v[10:11], v[10:11], v[242:243] op_sel_hi:[1,0]
	v_pk_mul_f32 v[8:9], v[8:9], v[242:243] op_sel_hi:[1,0]
	v_pk_mul_f32 v[6:7], v[6:7], v[242:243] op_sel_hi:[1,0]
	v_pk_mul_f32 v[4:5], v[4:5], v[242:243] op_sel_hi:[1,0]
	v_pk_mul_f32 v[22:23], v[2:3], v[242:243] op_sel_hi:[1,0]
	v_pk_mul_f32 v[16:17], v[0:1], v[242:243] op_sel_hi:[1,0]
	v_cvt_pk_bf16_f32 v0, v12, v13
	v_cvt_pk_bf16_f32 v1, v14, v15
	v_cvt_pk_bf16_f32 v2, v8, v9
	v_cvt_pk_bf16_f32 v3, v10, v11
	global_store_dwordx4 v[20:21], v[0:3], off
	s_nop 1
	v_cvt_pk_bf16_f32 v0, v4, v5
	v_cvt_pk_bf16_f32 v1, v6, v7
	v_cvt_pk_bf16_f32 v2, v16, v17
	v_cvt_pk_bf16_f32 v3, v22, v23
	global_store_dwordx4 v[18:19], v[0:3], off offset:256
	s_cbranch_vccnz .LBB0_1149
	s_andn2_b64 vcc, exec, s[8:9]
	s_cbranch_vccnz .LBB0_1148
	s_barrier
	s_branch .LBB0_1148
